# block loops: one workgroup barrier per two K/V blocks (pairs share a barrier, P V no longer deferred, pair DMA issued at the pair boundary)
# speedup vs baseline: 1.0049x; 1.0023x over previous
; #define NSA_LD1(jj) do { kr = *(const bf16x8*)((const char*)Kt + (size_t)(jj) * 8192 + kgo); vr = *(const bf16x8*)((const char*)Vt + (jj) * 128 + vgo); } while (0)
; #define NSA_ST1(st_, half_) do { LAS bf16_t* nx_ = stage + (st_) * 18432 + (half_) * 9216 + soff; *(LAS bf16x8*)nx_ = kr; *(LAS bf16x8*)(nx_ + 4608) = vr; } while (0)
; template <int MODE> ...
;     ...
;     bf16x8 kr, vr;
;     NSA_LD1(j0); NSA_ST1(0, 0);
;     if (j0 + 1 <= qb) { NSA_LD1(j0 + 1); NSA_ST1(0, 1); }
;     __syncthreads();
;     for (int jA = j0, pp = 0; jA <= qb; jA += 2, pp ^= 1) {
;       for (int sub = 0; sub < 2; ++sub) {
;         const int j = jA + sub; if (j > qb) break;
;         const bool pre = j + 2 <= qb;
;         if (pre) NSA_LD1(j + 2);
.Lnsa_blk_loop:
	s_cmp_eq_u32 s57, 0
	s_cbranch_scc0 .Lnsa_dnotfirst_9
	s_mov_b32 s14, 2
	s_min_u32 s15, s14, s19
	v_readlane_b32 s0, v179, s15
	v_readlane_b32 s1, v228, s15
	s_cmp_lt_u32 s15, 64
	s_cselect_b32 s95, s0, s1
	s_and_b32 s73, s95, 255
	s_and_b32 s0, s14, 3
	s_lshl_b32 s0, s0, 14
	s_add_i32 s0, s0, s33
	s_lshl_b32 s1, s73, 13
	s_add_u32 s70, s66, s1
	s_addc_u32 s71, s67, 0
	s_mov_b32 m0, s0
	s_lshl_b32 s1, s73, 7
	global_load_lds_dwordx4 v174, s[70:71]
	s_add_u32 s70, s68, s1
	s_addc_u32 s71, s69, 0
	s_add_i32 m0, s0, 8192
	s_add_i32 s1, s14, 0
	global_load_lds_dwordx4 v175, s[70:71]
	s_branch .Lnsa_ddone_10
.Lnsa_dnotfirst_9:
	s_bitcmp1_b32 s57, 0
	s_cbranch_scc0 .Lnsa_ddone_10
	s_add_i32 s14, s57, 2
	s_min_u32 s15, s14, s19
	v_readlane_b32 s0, v179, s15
	v_readlane_b32 s1, v228, s15
	s_cmp_lt_u32 s15, 64
	s_cselect_b32 s95, s0, s1
	s_and_b32 s73, s95, 255
	s_and_b32 s0, s14, 3
	s_lshl_b32 s0, s0, 14
	s_add_i32 s0, s0, s33
	s_lshl_b32 s1, s73, 13
	s_add_u32 s70, s66, s1
	s_addc_u32 s71, s67, 0
	s_mov_b32 m0, s0
	s_lshl_b32 s1, s73, 7
	global_load_lds_dwordx4 v174, s[70:71]
	s_add_u32 s70, s68, s1
	s_addc_u32 s71, s69, 0
	s_add_i32 m0, s0, 8192
	s_add_i32 s1, s14, 0
	global_load_lds_dwordx4 v175, s[70:71]
	s_add_i32 s14, s57, 3
	s_min_u32 s15, s14, s19
	v_readlane_b32 s0, v179, s15
	v_readlane_b32 s1, v228, s15
	s_cmp_lt_u32 s15, 64
	s_cselect_b32 s74, s0, s1
	s_and_b32 s73, s74, 255
	s_and_b32 s0, s14, 3
	s_lshl_b32 s0, s0, 14
	s_add_i32 s0, s0, s33
	s_lshl_b32 s1, s73, 13
	s_add_u32 s70, s66, s1
	s_addc_u32 s71, s67, 0
	s_mov_b32 m0, s0
	s_lshl_b32 s1, s73, 7
	global_load_lds_dwordx4 v174, s[70:71]
	s_add_u32 s70, s68, s1
	s_addc_u32 s71, s69, 0
	s_add_i32 m0, s0, 8192
	s_add_i32 s1, s14, 0
	global_load_lds_dwordx4 v175, s[70:71]

; #define LAS __attribute__((address_space(3)))
; #define CBAR() asm volatile("" ::: "memory")
; #define MFMA16(a, b, c) __builtin_amdgcn_mfma_f32_16x16x32_bf16(a, b, c, 0, 0, 0)
; template <int MODE> ...
;     ...
;                 for (int ks = 0; ks < 2; ++ks) { const bf16x8 aP = *(const LAS bf16x8*)(Pb + r16 * 72 + ks * 32 + q4 * 8);
; #pragma unroll
;                     for (int nt = 0; nt < 4; ++nt) os[tile][nt] = MFMA16(aP, *(const LAS bf16x8*)(Vs + (nt * 16 + r16) * 72 + ks * 32 + q4 * 8), os[tile][nt]); }
;                 CBAR();
.Lnsa_blkend_14:
	s_cmp_eq_u32 s43, 0
	s_cbranch_scc1 .Lnsa_pvnone_23
	ds_read_b128 v[50:53], v172 offset:0
	ds_read_b128 v[54:57], v173 offset:0
	ds_read_b128 v[58:61], v172 offset:2048
	ds_read_b128 v[62:65], v173 offset:2048
	s_cmp_eq_u32 s43, 3
	s_cbranch_scc0 .Lnsa_pvone_24
	s_waitcnt lgkmcnt(2)
	v_mfma_f32_16x16x32_bf16 v[2:5], v[50:53], v[82:85], v[2:5]
	v_mfma_f32_16x16x32_bf16 v[2:5], v[54:57], v[86:89], v[2:5]
	v_mfma_f32_16x16x32_bf16 v[18:21], v[50:53], v[90:93], v[18:21]
	v_mfma_f32_16x16x32_bf16 v[18:21], v[54:57], v[94:97], v[18:21]
	ds_read_b128 v[50:53], v172 offset:4096
	ds_read_b128 v[54:57], v173 offset:4096
	s_waitcnt lgkmcnt(2)
	v_mfma_f32_16x16x32_bf16 v[6:9], v[58:61], v[82:85], v[6:9]
	v_mfma_f32_16x16x32_bf16 v[6:9], v[62:65], v[86:89], v[6:9]
	v_mfma_f32_16x16x32_bf16 v[22:25], v[58:61], v[90:93], v[22:25]
	v_mfma_f32_16x16x32_bf16 v[22:25], v[62:65], v[94:97], v[22:25]
	ds_read_b128 v[58:61], v172 offset:6144
	ds_read_b128 v[62:65], v173 offset:6144
	s_waitcnt lgkmcnt(2)
	v_mfma_f32_16x16x32_bf16 v[10:13], v[50:53], v[82:85], v[10:13]
	v_mfma_f32_16x16x32_bf16 v[10:13], v[54:57], v[86:89], v[10:13]
	v_mfma_f32_16x16x32_bf16 v[26:29], v[50:53], v[90:93], v[26:29]
	v_mfma_f32_16x16x32_bf16 v[26:29], v[54:57], v[94:97], v[26:29]
	s_waitcnt lgkmcnt(0)
	v_mfma_f32_16x16x32_bf16 v[14:17], v[58:61], v[82:85], v[14:17]
	v_mfma_f32_16x16x32_bf16 v[14:17], v[62:65], v[86:89], v[14:17]
	v_mfma_f32_16x16x32_bf16 v[30:33], v[58:61], v[90:93], v[30:33]
	v_mfma_f32_16x16x32_bf16 v[30:33], v[62:65], v[94:97], v[30:33]
	s_branch .Lnsa_pvend_26

; template <int MODE> ...
;     ...
;     for (int jA = j0, pp = 0; jA <= qb; jA += 2, pp ^= 1) {
;       for (int sub = 0; sub < 2; ++sub) {
;         const int j = jA + sub; if (j > qb) break;
;         const bool pre = j + 2 <= qb;
;         if (pre) NSA_LD1(j + 2);
;         const LAS bf16_t* Ks = stage + pp * 18432 + sub * 9216; const LAS bf16_t* Vs = Ks + 4608;
;         const bool far = MODE == 0 && (qb - j >= 17);
; #pragma unroll
;         for (int tile = 0; tile < 2; ++tile) {
;             const int tl0 = wave * 8 + tile * 4, t0 = qb * 64 + tl0;
;             unsigned mb[4] = {1u, 1u, 1u, 1u};
;             if (MODE == 0) {
; #pragma unroll
;                 for (int i = 0; i < 4; ++i) mb[i] = (masks[(tl0 + i) * 4 + (j >> 5)] >> (j & 31)) & 1u; }
;             if (MODE == 1 || __builtin_amdgcn_readfirstlane((int)(mb[0] | mb[1] | mb[2] | mb[3]))) {
;                 f32x4 sc[4];
; #pragma unroll
;                 for (int cc = 0; cc < 4; ++cc) { const LAS bf16_t* kp = Ks + (cc * 16 + r16) * 72 + q4 * 8;
;                     sc[cc] = MFMA16(aq[tile][0], *(const LAS bf16x8*)kp, z4); sc[cc] = MFMA16(aq[tile][1], *(const LAS bf16x8*)(kp + 32), sc[cc]); }
;                 if (far) {
; #pragma unroll
;                     for (int cc = 0; cc < 4; ++cc)
; #pragma unroll
;                         for (int i = 0; i < 4; ++i) { const float p = mb[i] ? ex2(sc[cc][i] + bfar) : 0.f; ls[tile][i] += p; Pb[(4 * q4 + i) * 72 + cc * 16 + r16] = tobf(p); }
;                 } else {
; #pragma unroll
;                     for (int cc = 0; cc < 4; ++cc) { const int pos = j * 64 + cc * 16 + r16;
; #pragma unroll
;                         for (int i = 0; i < 4; ++i) { const int dist = t0 + i - pos; const bool ok = MODE ? ((unsigned)dist < 512u) : (dist >= 0 && mb[i]);
;                             const float p = ok ? ex2(sc[cc][i] + bt[clampd(dist)]) : 0.f; ls[tile][i] += p; Pb[(4 * q4 + i) * 72 + cc * 16 + r16] = tobf(p); } }
;                 }
;                 CBAR();
; #pragma unroll
;                 for (int ks = 0; ks < 2; ++ks) { const bf16x8 aP = *(const LAS bf16x8*)(Pb + r16 * 72 + ks * 32 + q4 * 8);
; #pragma unroll
;                     for (int nt = 0; nt < 4; ++nt) os[tile][nt] = MFMA16(aP, *(const LAS bf16x8*)(Vs + (nt * 16 + r16) * 72 + ks * 32 + q4 * 8), os[tile][nt]); }
;                 CBAR();
;             }
;         }
.Lnsa_pvnone_23:
	s_add_i32 s0, s57, 1
	s_bitcmp1_b32 s57, 0
	s_cbranch_scc0 .Lnsa_pbar_27
	s_cmp_eq_u32 s0, s92
	s_cbranch_scc0 .Lnsa_pnobar_28
.Lnsa_pbar_27:
	s_waitcnt vmcnt(0) lgkmcnt(0)
	s_barrier
.Lnsa_pnobar_28:
	s_mov_b32 s93, s94
	s_mov_b32 s94, s95
	s_mov_b32 s95, s74
	s_add_i32 s57, s57, 1
	s_cmp_lt_u32 s57, s92
	s_cbranch_scc1 .Lnsa_blk_loop
	s_cmp_lg_u32 s54, 0
	s_cbranch_scc1 .Lnsa_noearly_29
	s_add_u32 s66, s30, 0x35900000
	s_addc_u32 s67, s31, 0
	s_add_u32 s68, s30, 0x36900000
	s_addc_u32 s69, s31, 0
	s_lshr_b32 s15, s97, 13
	s_lshl_b32 s15, s15, 2
	s_and_b32 s1, s88, 3
	s_or_b32 s15, s15, s1
	s_lshl_b32 s15, s15, 20
	s_add_u32 s66, s66, s15
	s_addc_u32 s67, s67, 0
	s_add_u32 s68, s68, s15
	s_addc_u32 s69, s69, 0
	s_lshl_b32 s33, s80, 7
	s_add_i32 s33, s33, 56384
	s_add_i32 s14, s18, -8
	s_max_i32 s14, s14, 0
	s_mov_b32 s15, 0
	s_and_b32 s0, s15, 3
	s_lshl_b32 s0, s0, 14
	s_add_i32 s0, s0, s33
	s_lshl_b32 s1, s14, 13
	s_add_u32 s70, s66, s1
	s_addc_u32 s71, s67, 0
	s_mov_b32 m0, s0
	s_lshl_b32 s1, s14, 7
	global_load_lds_dwordx4 v174, s[70:71]
	s_add_u32 s70, s68, s1
	s_addc_u32 s71, s69, 0
	s_add_i32 m0, s0, 8192
	s_add_i32 s1, s15, 0
	global_load_lds_dwordx4 v175, s[70:71]
	s_add_i32 s14, s14, 1
	s_min_i32 s14, s14, s18
	s_mov_b32 s15, 1
	s_and_b32 s0, s15, 3
	s_lshl_b32 s0, s0, 14
	s_add_i32 s0, s0, s33
	s_lshl_b32 s1, s14, 13
	s_add_u32 s70, s66, s1
	s_addc_u32 s71, s67, 0
	s_mov_b32 m0, s0
	s_lshl_b32 s1, s14, 7
	global_load_lds_dwordx4 v174, s[70:71]
	s_add_u32 s70, s68, s1
	s_addc_u32 s71, s69, 0
	s_add_i32 m0, s0, 8192
	s_add_i32 s1, s15, 0
	global_load_lds_dwordx4 v175, s[70:71]
